# MoBA unit prologue: K2 LDS-DMA piece issued together with K0/V0/K1 (before the gate) so it has landed by the post-step-0 wait; Q waits vmcnt(4)
# baseline (speedup 1.0000x reference)
;   #define DMA_K(t,slot) glds16(ksrc+(long)(TKT(t))*KVBLK*D,(unsigned)__builtin_amdgcn_readfirstlane(kdst+(slot)))
;   #define DMA_V(t,slot) glds16(vsrc+(long)(TKT(t))*KVBLK*D,(unsigned)__builtin_amdgcn_readfirstlane(vdst+(slot)))
; template<int THRL> __device__ __forceinline__ void attn_unit(int b,int h,int qb,const bf16*Q,const bf16*__restrict__ K,const bf16*__restrict__ V,bf16*O,char*shm,const float*KMg,const float*rel_bias,bool newhead,bf16x8 (&qr)[4],const bf16*Qnext){
;     ...
;   const bf16*Qw=Q+(rowbase+q0+wid*QBLK)*DM+h*D;
;   const bf16*Kh=K+(long)(b*NHEAD+h)*SEQ*D,*Vh=V+(long)(b*NHEAD+h)*SEQ*D;
;   const unsigned lds0=(unsigned)(uintptr_t)shm;
;   float*wsf=(float*)(shm+LDS_WS)+wid*64;
;   const bf16*ksrc=Kh+(long)lane*D+wid*8;
;   const bf16*vsrc=Vh+(long)(16*(wid&3)+(lane>>2))*D+(wid>>2)*32+(lane&3)*8;
;   const unsigned kdst=lds0+LDS_K+wid*1024, vdst=lds0+LDS_V+wid*1024;
;     ...
;   const int vb0=(int)(lds0+LDS_V)+((lane>>4)&1)*32+(lane&3)*8+(4*hi+((lane&15)>>2))*64;
;   const char*Kbase=shm+LDS_K; bf16x8 kf[8];
;   const lds_cptr shm3=(lds_cptr)shm; const lds_cptr kp0=shm3+LDS_K+hi*1024+r32*16; const lds_cptr vp0=shm3+LDS_V+((lane>>4)&1)*32+(lane&3)*8+(4*hi+((lane&15)>>2))*64;
;   const int NT=(q0+QB)/KVBLK;
;   DMA_K(0,0);DMA_V(0,0);DMA_K(1,SLOTB);
;     ...
;   DMA_K(2,2*SLOTB);
.LBB0_447:
	s_bfe_u32 s20, s43, 0x30008
	s_lshl_b32 s5, s20, 8
	s_lshl_b64 s[6:7], s[6:7], 18
	v_readlane_b32 s8, v254, 18
	s_add_u32 s8, s8, s6
	v_readlane_b32 s9, v254, 19
	s_addc_u32 s9, s9, s7
	v_readlane_b32 s10, v254, 16
	s_add_u32 s6, s10, s6
	v_readlane_b32 s10, v254, 17
	v_lshlrev_b32_e32 v2, 7, v238
	v_mov_b32_e32 v3, v0
	s_addc_u32 s7, s10, s7
	v_lshl_add_u64 v[2:3], s[8:9], 0, v[2:3]
	s_lshl_b32 s8, s77, 3
	s_ashr_i32 s9, s8, 31
	v_lshl_add_u64 v[218:219], s[8:9], 1, v[2:3]
	s_lshl_b32 s8, s77, 4
	v_lshrrev_b32_e32 v1, 2, v238
	v_and_or_b32 v1, s8, 48, v1
	v_lshlrev_b32_e32 v2, 7, v1
	v_mov_b32_e32 v3, v0
	v_lshl_add_u64 v[2:3], s[6:7], 0, v[2:3]
	s_ashr_i32 s6, s42, 3
	s_andn2_b32 s6, s6, 31
	s_ashr_i32 s7, s6, 31
	s_lshl_b32 s24, s77, 10
	s_cmp_lg_u32 0, -1
	v_lshl_add_u64 v[2:3], s[6:7], 1, v[2:3]
	s_cselect_b32 s6, 0, 0
	s_add_i32 s33, s24, s6
	s_add_i32 s6, s5, 0x100
	s_lshr_b32 s28, s6, 6
	v_and_b32_e32 v240, 24, v239
	s_add_i32 s82, s28, -4
	s_mov_b32 s83, s59
	v_lshlrev_b32_e32 v4, 1, v240
	v_mov_b32_e32 v5, v0
	s_lshl_b64 s[6:7], s[82:83], 13
	v_lshl_add_u64 v[220:221], v[2:3], 0, v[4:5]
	v_lshl_add_u64 v[2:3], v[218:219], 0, s[6:7]
	s_mov_b32 s8, m0
	s_mov_b32 m0, s33
	s_nop 0
	global_load_lds_dwordx4 v[2:3], off
	s_mov_b32 m0, s8
	s_add_i32 s10, s33, 0x6000
	v_lshl_add_u64 v[2:3], v[220:221], 0, s[6:7]
	s_mov_b32 s6, m0
	s_mov_b32 m0, s10
	s_nop 0
	global_load_lds_dwordx4 v[2:3], off
	s_mov_b32 m0, s6
	s_add_i32 s58, s28, -3
	s_lshl_b64 s[6:7], s[58:59], 13
	v_lshl_add_u64 v[2:3], v[218:219], 0, s[6:7]
	s_add_i32 s6, s33, 0x2000
	s_mov_b32 s7, m0
	s_mov_b32 m0, s6
	s_nop 0
	global_load_lds_dwordx4 v[2:3], off
	s_mov_b32 m0, s7
	s_add_i32 s6, s28, -2
	s_mov_b32 s7, s59
	s_lshl_b64 s[6:7], s[6:7], 13
	v_lshl_add_u64 v[2:3], v[218:219], 0, s[6:7]
	s_add_i32 s6, s33, 0x4000
	s_mov_b32 s8, m0
	s_mov_b32 m0, s6
	s_nop 0
	global_load_lds_dwordx4 v[2:3], off
	s_mov_b32 m0, s8
	s_cmp_eq_u32 s20, 0
	s_cselect_b64 s[6:7], -1, 0
	s_cmp_lg_u32 s20, 0
	s_cselect_b64 s[8:9], -1, 0
	v_mov_b32_e32 v223, 0
	s_and_b64 vcc, exec, s[6:7]
	s_cbranch_vccnz .LBB0_464
; template<int THRL> __device__ __forceinline__ void attn_unit(int b,int h,int qb,const bf16*Q,const bf16*__restrict__ K,const bf16*__restrict__ V,bf16*O,char*shm,const float*KMg,const float*rel_bias,bool newhead,bf16x8 (&qr)[4],const bf16*Qnext){
;     ...
;   if(qb>0){ float g[7];
;     #pragma unroll
;     for(int n=0;n<7;++n){ float a=0.f;
;       if(n<qb){
;         #pragma unroll
;         for(int d0=0;d0<4;++d0){ const h16x8v qv=__builtin_bit_cast(h16x8v,qr[d0]);
;           #pragma unroll
;           for(int j=0;j<8;++j)a+=(float)qv[j]*kml[n*64+16*d0+8*hi+j]; } }
;       { auto rr=__builtin_amdgcn_permlane32_swap(__float_as_uint(a),__float_as_uint(a),false,false); a=__uint_as_float(rr[0])+__uint_as_float(rr[1]); }
;       g[n]=(n<qb)?a:-INFINITY; }
	v_and_b32_e32 v1, 32, v17
	v_add_u32_e32 v1, 0, v1
	v_add_u32_e32 v1, 0x14800, v1
	ds_read_b128 v[2:5], v1
	ds_read_b128 v[6:9], v1 offset:16
	s_waitcnt vmcnt(4)
	v_cvt_f32_f16_e32 v30, v144
	v_cvt_f32_f16_sdwa v31, v144 dst_sel:DWORD dst_unused:UNUSED_PAD src0_sel:WORD_1
	v_cvt_f32_f16_e32 v32, v145
	s_waitcnt lgkmcnt(1)
	v_fma_mix_f32 v2, v2, v144, 0 op_sel_hi:[0,1,0]
	v_fma_mix_f32 v2, v3, v144, v2 op_sel:[0,1,0] op_sel_hi:[0,1,0]
	v_fma_mix_f32 v2, v4, v145, v2 op_sel_hi:[0,1,0]
	v_fma_mix_f32 v2, v5, v145, v2 op_sel:[0,1,0] op_sel_hi:[0,1,0]
	s_waitcnt lgkmcnt(0)
	v_fma_mix_f32 v2, v6, v146, v2 op_sel_hi:[0,1,0]
	v_fma_mix_f32 v2, v7, v146, v2 op_sel:[0,1,0] op_sel_hi:[0,1,0]
	v_fma_mix_f32 v6, v8, v147, v2 op_sel_hi:[0,1,0]
	ds_read_b128 v[2:5], v1 offset:64
	v_fma_mix_f32 v10, v9, v147, v6 op_sel:[0,1,0] op_sel_hi:[0,1,0]
	ds_read_b128 v[6:9], v1 offset:80
	v_cvt_f32_f16_sdwa v33, v145 dst_sel:DWORD dst_unused:UNUSED_PAD src0_sel:WORD_1
	v_cvt_f32_f16_e32 v34, v146
	s_waitcnt lgkmcnt(1)
	v_fma_mix_f32 v2, v2, v148, v10 op_sel_hi:[0,1,0]
	v_fma_mix_f32 v2, v3, v148, v2 op_sel:[0,1,0] op_sel_hi:[0,1,0]
	v_fma_mix_f32 v2, v4, v149, v2 op_sel_hi:[0,1,0]
	v_fma_mix_f32 v2, v5, v149, v2 op_sel:[0,1,0] op_sel_hi:[0,1,0]
	s_waitcnt lgkmcnt(0)
	v_fma_mix_f32 v2, v6, v150, v2 op_sel_hi:[0,1,0]
	v_fma_mix_f32 v2, v7, v150, v2 op_sel:[0,1,0] op_sel_hi:[0,1,0]
	v_fma_mix_f32 v6, v8, v151, v2 op_sel_hi:[0,1,0]
	ds_read_b128 v[2:5], v1 offset:128
	ds_read_b128 v[10:13], v1 offset:144
	v_fma_mix_f32 v6, v9, v151, v6 op_sel:[0,1,0] op_sel_hi:[0,1,0]
	v_cvt_f32_f16_sdwa v35, v146 dst_sel:DWORD dst_unused:UNUSED_PAD src0_sel:WORD_1
	v_cvt_f32_f16_e32 v36, v147
	s_waitcnt lgkmcnt(1)
	v_fma_mix_f32 v2, v2, v152, v6 op_sel_hi:[0,1,0]
	v_fma_mix_f32 v2, v3, v152, v2 op_sel:[0,1,0] op_sel_hi:[0,1,0]
	v_fma_mix_f32 v2, v4, v153, v2 op_sel_hi:[0,1,0]
	v_fma_mix_f32 v2, v5, v153, v2 op_sel:[0,1,0] op_sel_hi:[0,1,0]
	s_waitcnt lgkmcnt(0)
	v_fma_mix_f32 v2, v10, v154, v2 op_sel_hi:[0,1,0]
	v_fma_mix_f32 v2, v11, v154, v2 op_sel:[0,1,0] op_sel_hi:[0,1,0]
	v_fma_mix_f32 v6, v12, v155, v2 op_sel_hi:[0,1,0]
	ds_read_b128 v[2:5], v1 offset:192
	ds_read_b128 v[38:41], v1 offset:208
	v_fma_mix_f32 v12, v13, v155, v6 op_sel:[0,1,0] op_sel_hi:[0,1,0]
	v_cvt_f32_f16_sdwa v37, v147 dst_sel:DWORD dst_unused:UNUSED_PAD src0_sel:WORD_1
	v_cvt_f32_f16_e32 v26, v148
	s_waitcnt lgkmcnt(1)
	v_fma_mix_f32 v2, v2, v156, v12 op_sel_hi:[0,1,0]
	v_fma_mix_f32 v2, v3, v156, v2 op_sel:[0,1,0] op_sel_hi:[0,1,0]
	v_fma_mix_f32 v2, v4, v157, v2 op_sel_hi:[0,1,0]
	v_fma_mix_f32 v4, v5, v157, v2 op_sel:[0,1,0] op_sel_hi:[0,1,0]
	s_waitcnt lgkmcnt(0)
	v_fma_mix_f32 v4, v38, v158, v4 op_sel_hi:[0,1,0]
	v_fma_mix_f32 v14, v39, v158, v4 op_sel:[0,1,0] op_sel_hi:[0,1,0]
	v_cvt_f32_f16_sdwa v27, v148 dst_sel:DWORD dst_unused:UNUSED_PAD src0_sel:WORD_1
	v_cvt_f32_f16_e32 v28, v149
	v_cvt_f32_f16_sdwa v29, v149 dst_sel:DWORD dst_unused:UNUSED_PAD src0_sel:WORD_1
	v_cvt_f32_f16_e32 v22, v150
	v_cvt_f32_f16_sdwa v23, v150 dst_sel:DWORD dst_unused:UNUSED_PAD src0_sel:WORD_1
	v_cvt_f32_f16_e32 v24, v151
	v_cvt_f32_f16_sdwa v25, v151 dst_sel:DWORD dst_unused:UNUSED_PAD src0_sel:WORD_1
	v_cvt_f32_f16_e32 v18, v152
	v_cvt_f32_f16_sdwa v19, v152 dst_sel:DWORD dst_unused:UNUSED_PAD src0_sel:WORD_1
	v_cvt_f32_f16_e32 v20, v153
	v_cvt_f32_f16_sdwa v21, v153 dst_sel:DWORD dst_unused:UNUSED_PAD src0_sel:WORD_1
	v_cvt_f32_f16_sdwa v9, v154 dst_sel:DWORD dst_unused:UNUSED_PAD src0_sel:WORD_1
	v_cvt_f32_f16_e32 v8, v154
	v_cvt_f32_f16_sdwa v11, v155 dst_sel:DWORD dst_unused:UNUSED_PAD src0_sel:WORD_1
	v_cvt_f32_f16_e32 v10, v155
	v_cvt_f32_f16_sdwa v7, v156 dst_sel:DWORD dst_unused:UNUSED_PAD src0_sel:WORD_1
	v_cvt_f32_f16_e32 v6, v156
	v_cvt_f32_f16_sdwa v13, v157 dst_sel:DWORD dst_unused:UNUSED_PAD src0_sel:WORD_1
	v_cvt_f32_f16_e32 v12, v157
	v_cvt_f32_f16_sdwa v3, v158 dst_sel:DWORD dst_unused:UNUSED_PAD src0_sel:WORD_1
	v_cvt_f32_f16_e32 v2, v158
	v_cvt_f32_f16_sdwa v5, v159 dst_sel:DWORD dst_unused:UNUSED_PAD src0_sel:WORD_1
	v_cvt_f32_f16_e32 v4, v159
	v_fma_mix_f32 v14, v40, v159, v14 op_sel_hi:[0,1,0]
	v_fma_mix_f32 v14, v41, v159, v14 op_sel:[0,1,0] op_sel_hi:[0,1,0]
	v_mov_b32_e32 v15, v14
	s_nop 1
	v_permlane32_swap_b32_e32 v14, v15
	v_mov_b32_e32 v38, 0
	s_cmp_eq_u32 s20, 1
	v_mov_b32_e32 v39, 0
	s_cbranch_scc1 .LBB0_450
	ds_read_b128 v[40:43], v1 offset:256
	ds_read_b128 v[44:47], v1 offset:272
	s_waitcnt lgkmcnt(1)
	v_fma_f32 v39, v40, v30, 0
	v_fmac_f32_e32 v39, v41, v31
	v_fmac_f32_e32 v39, v42, v32
	v_fmac_f32_e32 v39, v43, v33
	ds_read_b128 v[40:43], v1 offset:320
	s_waitcnt lgkmcnt(1)
	v_fmac_f32_e32 v39, v44, v34
	v_fmac_f32_e32 v39, v45, v35
	v_fmac_f32_e32 v39, v46, v36
	v_fmac_f32_e32 v39, v47, v37
	s_waitcnt lgkmcnt(0)
	v_fmac_f32_e32 v39, v40, v26
	v_fmac_f32_e32 v39, v41, v27
	v_fmac_f32_e32 v39, v42, v28
	v_fmac_f32_e32 v39, v43, v29
	ds_read_b128 v[40:43], v1 offset:336
	s_waitcnt lgkmcnt(0)
	v_fmac_f32_e32 v39, v40, v22
	v_fmac_f32_e32 v39, v41, v23
	v_fmac_f32_e32 v39, v42, v24
	v_fmac_f32_e32 v39, v43, v25
	ds_read_b128 v[40:43], v1 offset:384
	s_waitcnt lgkmcnt(0)
	v_fmac_f32_e32 v39, v40, v18
	v_fmac_f32_e32 v39, v41, v19
	v_fmac_f32_e32 v39, v42, v20
	v_fmac_f32_e32 v39, v43, v21
	ds_read_b128 v[40:43], v1 offset:400
	s_waitcnt lgkmcnt(0)
	v_pk_mul_f32 v[40:41], v[40:41], v[8:9]
	s_nop 0
	v_add_f32_e32 v39, v39, v40
	v_add_f32_e32 v39, v39, v41
	v_pk_mul_f32 v[40:41], v[42:43], v[10:11]
	s_nop 0
	v_add_f32_e32 v39, v39, v40
	v_add_f32_e32 v39, v39, v41
	ds_read_b128 v[40:43], v1 offset:448
	s_waitcnt lgkmcnt(0)
	v_pk_mul_f32 v[40:41], v[40:41], v[6:7]
	s_nop 0
	v_add_f32_e32 v39, v39, v40
	v_add_f32_e32 v39, v39, v41
	v_pk_mul_f32 v[40:41], v[42:43], v[12:13]
	s_nop 0
	v_add_f32_e32 v39, v39, v40
	v_add_f32_e32 v39, v39, v41
	ds_read_b128 v[40:43], v1 offset:464
	s_waitcnt lgkmcnt(0)
	v_pk_mul_f32 v[40:41], v[40:41], v[2:3]
	s_nop 0
	v_add_f32_e32 v39, v39, v40
	v_add_f32_e32 v39, v39, v41
	v_pk_mul_f32 v[40:41], v[42:43], v[4:5]
	s_nop 0
	v_add_f32_e32 v39, v39, v40
	v_add_f32_e32 v39, v39, v41

; #define WAIT_BAR(N) asm volatile("s_waitcnt vmcnt(" #N ") lgkmcnt(0)\n\ts_barrier":::"memory")
;   #define DMA_K(t,slot) glds16(ksrc+(long)(TKT(t))*KVBLK*D,(unsigned)__builtin_amdgcn_readfirstlane(kdst+(slot)))
;   #define START(P0,P1) do{ const float rm=rowmax(P0,P1); resc=false; \
;     { const float dl=rm; mhat=fadd_s(mhat,dl); \
;       _Pragma("unroll") for(int r=0;r<16;++r){P0[r]=fsub_s(P0[r],dl);P1[r]=fsub_s(P1[r],dl);} \
;       _Pragma("unroll") for(int r=0;r<16;++r)negm[r]=-mhat; asm volatile("":"+v"(negm)); } \
;     _Pragma("unroll") for(int r=0;r<16;++r)P0[r]=__builtin_amdgcn_exp2f(P0[r]); }while(0)
;   #define CMASK(P0,P1,t) do{ if(mixed){ const unsigned sel_=sel; if(((sel_>>(TKT(t)>>2))&1u)==0u){ _Pragma("unroll") for(int r=0;r<16;++r){P0[r]=-INFINITY;P1[r]=-INFINITY;} } } }while(0)
; template<int THRL> __device__ __forceinline__ void attn_unit(int b,int h,int qb,const bf16*Q,const bf16*__restrict__ K,const bf16*__restrict__ V,bf16*O,char*shm,const float*KMg,const float*rel_bias,bool newhead,bf16x8 (&qr)[4],const bf16*Qnext){
;     ...
;   float mhat=0.f,l_reg=0.f;f32x16 o[2];o[0]=f32x16{};o[1]=f32x16{};f32x16 negm=f32x16{};asm volatile("":"+v"(negm));
;   const int qrel=wid*QBLK+r32;
;     ...
;   bool resc=false;
;     ...
;   f32x16 pA0,pA1,pB0,pB1;
;   int sl_prev=0,sl_cur=0,sl_next=SLOTB;
;     ...
;   DMA_K(2,2*SLOTB);
;   WAIT_BAR(3);
;   qkt(pA0,pA1,Kbase,qr,negm,r32,hi);asm volatile("s_nop 15\n\ts_nop 7":"+v"(pA0),"+v"(pA1));CMASK(pA0,pA1,0);
;   START(pA0,pA1);
;   _Pragma("unroll") for(int r=0;r<16;++r)pA1[r]=__builtin_amdgcn_exp2f(pA1[r]);
;   WAIT_BAR(0);
.LBB0_466:
	s_add_i32 s58, s28, -2
	s_lshl_b32 s71, s77, 5
	s_lshl_b64 s[16:17], s[58:59], 13
	v_mov_b32_e32 v14, v0
	s_waitcnt vmcnt(4)
	v_mov_b32_e32 v15, v0
	s_cmp_lg_u32 0, -1
	v_add3_u32 v245, 0, v1, v2
	v_mov_b32_e32 v1, v0
	v_mov_b32_e32 v2, v0
	v_mov_b32_e32 v3, v0
	v_mov_b32_e32 v4, v0
	v_mov_b32_e32 v5, v0
	v_mov_b32_e32 v6, v0
	v_mov_b32_e32 v7, v0
	v_mov_b32_e32 v8, v0
	v_mov_b32_e32 v9, v0
	v_mov_b32_e32 v10, v0
	v_mov_b32_e32 v11, v0
	v_mov_b32_e32 v12, v0
	v_mov_b32_e32 v13, v0
	v_mov_b64_e32 v[32:33], v[14:15]
	s_cselect_b32 s12, 0, 0
	v_mov_b64_e32 v[30:31], v[12:13]
	v_mov_b64_e32 v[28:29], v[10:11]
	v_mov_b64_e32 v[26:27], v[8:9]
	v_mov_b64_e32 v[24:25], v[6:7]
	v_mov_b64_e32 v[22:23], v[4:5]
	v_mov_b64_e32 v[20:21], v[2:3]
	v_mov_b64_e32 v[18:19], v[0:1]
	s_add_i32 s12, s12, s24
	s_add_i32 s13, s12, 0x4000
	s_waitcnt vmcnt(3) lgkmcnt(0)
	s_barrier
	ds_read_b128 v[2:5], v245
	ds_read_b128 v[6:9], v245 offset:512
	s_waitcnt lgkmcnt(1)
	v_mfma_f32_32x32x16_f16 v[34:49], v[2:5], v[144:147], v[18:33]
	v_lshlrev_b32_e32 v1, 1, v17
	v_lshlrev_b32_e32 v140, 2, v241
	v_and_b32_e32 v1, 32, v1
	s_lshl_b32 s13, s82, 6
	v_or_b32_e32 v14, s71, v242
	s_addk_i32 s13, 0x17f
	s_add_i32 s26, s28, -1
	s_waitcnt lgkmcnt(0)
	v_mfma_f32_32x32x16_f16 v[18:33], v[6:9], v[144:147], v[18:33]
	ds_read_b128 v[2:5], v245 offset:2048
	ds_read_b128 v[6:9], v245 offset:2560
	s_mov_b32 s27, s59
	s_lshl_b64 s[26:27], s[26:27], 13
	s_add_i32 s12, s12, 0x8000
	v_mov_b64_e32 v[234:235], 0x400
	s_waitcnt lgkmcnt(1)
	v_mfma_f32_32x32x16_f16 v[34:49], v[2:5], v[148:151], v[34:49]
	s_waitcnt lgkmcnt(0)
	v_mfma_f32_32x32x16_f16 v[18:33], v[6:9], v[148:151], v[18:33]
	ds_read_b128 v[2:5], v245 offset:4096
	ds_read_b128 v[6:9], v245 offset:4608
	s_waitcnt lgkmcnt(1)
	v_mfma_f32_32x32x16_f16 v[34:49], v[2:5], v[152:155], v[34:49]
	s_waitcnt lgkmcnt(0)
	v_mfma_f32_32x32x16_f16 v[18:33], v[6:9], v[152:155], v[18:33]
	ds_read_b128 v[2:5], v245 offset:6144
	ds_read_b128 v[6:9], v245 offset:6656
	s_waitcnt lgkmcnt(1)
	v_mfma_f32_32x32x16_f16 v[34:49], v[2:5], v[156:159], v[34:49]
	v_lshrrev_b32_e32 v2, 2, v17
	v_and_or_b32 v2, v2, 3, v140
	v_lshlrev_b32_e32 v243, 6, v2
	v_add_u32_e32 v2, 0, v1
	v_add3_u32 v246, v2, v240, v243
	v_add_u32_e32 v17, s5, v14
	v_add_u32_e32 v2, s13, v140
	v_sub_u32_e32 v2, v2, v17
	v_and_b32_e32 v3, 3, v2
	v_lshlrev_b32_e32 v2, 2, v2
	v_mul_u32_u24_e32 v3, 0xa00, v3
	v_and_b32_e32 v2, -16, v2
	v_readlane_b32 s13, v255, 24
	s_waitcnt lgkmcnt(0)
	v_mfma_f32_32x32x16_f16 v[18:33], v[6:9], v[156:159], v[18:33]
	s_nop 15
	s_nop 7
	v_add3_u32 v15, s13, v3, v2
	ds_read_b128 v[2:5], v15
	ds_read_b128 v[6:9], v15 offset:32
	ds_read_b128 v[10:13], v15 offset:128
	ds_read_b128 v[50:53], v15 offset:160
	ds_read_b128 v[54:57], v15 offset:64
	ds_read_b128 v[58:61], v15 offset:96
	ds_read_b128 v[62:65], v15 offset:192
	ds_read_b128 v[66:69], v15 offset:224
	s_waitcnt lgkmcnt(7)
	v_add_f32_e32 v2, v34, v2
	s_waitcnt lgkmcnt(5)
	v_add_f32_e32 v10, v18, v10
	v_add_f32_e32 v3, v35, v3
	v_max3_f32 v15, v2, v3, v10
	v_add_f32_e32 v11, v19, v11
	v_add_f32_e32 v4, v36, v4
	v_add_f32_e32 v12, v20, v12
	v_add_f32_e32 v5, v37, v5
	v_add_f32_e32 v13, v21, v13
	v_add_f32_e32 v6, v38, v6
	v_max3_f32 v38, v4, v5, v11
	v_max3_f32 v15, v15, v12, v13
	v_add_f32_e32 v7, v39, v7
	v_add_f32_e32 v8, v40, v8
	v_add_f32_e32 v9, v41, v9
	v_max3_f32 v15, v15, v6, v7
	v_max3_f32 v38, v38, v8, v9
	s_waitcnt lgkmcnt(4)
	v_add_f32_e32 v18, v22, v50
	v_add_f32_e32 v19, v23, v51
	v_add_f32_e32 v20, v24, v52
	v_add_f32_e32 v21, v25, v53
	v_max3_f32 v15, v15, v18, v19
	v_max3_f32 v38, v38, v20, v21
	s_waitcnt lgkmcnt(3)
	v_add_f32_e32 v22, v42, v54
	s_waitcnt lgkmcnt(1)
	v_add_f32_e32 v23, v26, v62
	v_add_f32_e32 v24, v43, v55
	v_add_f32_e32 v25, v27, v63
	v_add_f32_e32 v26, v44, v56
	v_add_f32_e32 v27, v28, v64
	v_add_f32_e32 v28, v45, v57
	v_max3_f32 v15, v15, v22, v24
	v_max3_f32 v38, v38, v26, v28
	v_add_f32_e32 v29, v29, v65
	v_max3_f32 v15, v15, v23, v25
	v_max3_f32 v38, v38, v27, v29
	v_add_f32_e32 v34, v46, v58
	v_add_f32_e32 v35, v47, v59
	v_add_f32_e32 v36, v48, v60
	v_add_f32_e32 v37, v49, v61
	v_max3_f32 v15, v15, v34, v35
	v_max3_f32 v38, v38, v36, v37
	s_waitcnt lgkmcnt(0)
	v_add_f32_e32 v30, v30, v66
	v_add_f32_e32 v31, v31, v67
	v_add_f32_e32 v32, v32, v68
	v_add_f32_e32 v33, v33, v69
	v_max3_f32 v15, v15, v30, v31
	v_max3_f32 v38, v38, v32, v33
	s_nop 0
	v_max_f32_e32 v15, v15, v38
	s_nop 0
	v_mov_b32_e32 v38, v15
	s_nop 1
	v_permlane32_swap_b32_e32 v15, v38
	v_max_f32_e32 v38, v15, v38
	s_nop 0
	v_add_f32_e32 v15, v0, v38
	v_sub_f32_e32 v39, v2, v38
	v_sub_f32_e32 v41, v3, v38
	v_lshl_add_u64 v[2:3], v[218:219], 0, s[26:27]
	v_xor_b32_e32 v64, 0x80000000, v15
	v_mov_b32_e32 v65, v64
	v_mov_b32_e32 v66, v64
	v_mov_b32_e32 v67, v64
	v_mov_b32_e32 v68, v64
	v_mov_b32_e32 v69, v64
	v_mov_b32_e32 v70, v64
	v_mov_b32_e32 v71, v64
	v_mov_b32_e32 v72, v64
	v_mov_b32_e32 v73, v64
	v_mov_b32_e32 v74, v64
	v_mov_b32_e32 v75, v64
	v_mov_b32_e32 v76, v64
	v_mov_b32_e32 v77, v64
	v_mov_b32_e32 v78, v64
	v_mov_b32_e32 v79, v64
	s_waitcnt vmcnt(0) lgkmcnt(0)
	s_barrier
; #define WAIT_BAR(N) asm volatile("s_waitcnt vmcnt(" #N ") lgkmcnt(0)\n\ts_barrier":::"memory")
;   #define DMA_K(t,slot) glds16(ksrc+(long)(TKT(t))*KVBLK*D,(unsigned)__builtin_amdgcn_readfirstlane(kdst+(slot)))
;   #define DMA_V(t,slot) glds16(vsrc+(long)(TKT(t))*KVBLK*D,(unsigned)__builtin_amdgcn_readfirstlane(vdst+(slot)))
;   #define ROT() do{sl_prev=sl_cur;sl_cur=sl_next;sl_next=(sl_next==(NSLOT-1)*SLOTB)?0:sl_next+SLOTB;}while(0)
; template<int THRL> __device__ __forceinline__ void attn_unit(int b,int h,int qb,const bf16*Q,const bf16*__restrict__ K,const bf16*__restrict__ V,bf16*O,char*shm,const float*KMg,const float*rel_bias,bool newhead,bf16x8 (&qr)[4],const bf16*Qnext){
;     ...
;   WAIT_BAR(0);
;   DMA_K(3,0);DMA_V(1,SLOTB);
;   ROT();
;   kload8(kf,kp0+sl_cur);
;   WAIT_BAR(2);
;   s16x4 vlo[8],vhi[8]; u32x4 pw0,pw1,pw2,pw3;
	s_mov_b32 s13, m0
	s_mov_b32 m0, s33
	s_nop 0
	global_load_lds_dwordx4 v[2:3], off
	s_mov_b32 m0, s13
	v_lshl_add_u64 v[2:3], s[22:23], 1, v[220:221]
	s_mov_b32 s13, m0
	s_mov_b32 m0, s12
	s_nop 0
	global_load_lds_dwordx4 v[2:3], off
	s_mov_b32 m0, s13
	v_sub_f32_e32 v40, v10, v38
	v_sub_f32_e32 v42, v11, v38
	v_sub_f32_e32 v43, v4, v38
	v_sub_f32_e32 v44, v12, v38
	v_sub_f32_e32 v45, v5, v38
	v_sub_f32_e32 v46, v13, v38
	ds_read_b128 v[2:5], v245 offset:8192
	ds_read_b128 v[10:13], v245 offset:8704
	ds_read_b128 v[58:61], v245 offset:10240
	ds_read_b128 v[84:87], v245 offset:10752
	ds_read_b128 v[88:91], v245 offset:12288
	ds_read_b128 v[92:95], v245 offset:12800
	ds_read_b128 v[96:99], v245 offset:14336
	ds_read_b128 v[100:103], v245 offset:14848
	v_sub_f32_e32 v37, v37, v38
	v_sub_f32_e32 v6, v6, v38
	v_sub_f32_e32 v18, v18, v38
	v_sub_f32_e32 v7, v7, v38
	v_sub_f32_e32 v19, v19, v38
	v_sub_f32_e32 v8, v8, v38
	v_sub_f32_e32 v20, v20, v38
	v_sub_f32_e32 v9, v9, v38
	v_sub_f32_e32 v21, v21, v38
	v_sub_f32_e32 v22, v22, v38
	v_sub_f32_e32 v23, v23, v38
	v_sub_f32_e32 v24, v24, v38
	v_sub_f32_e32 v25, v25, v38
	v_sub_f32_e32 v26, v26, v38
	v_sub_f32_e32 v27, v27, v38
	v_sub_f32_e32 v28, v28, v38
	v_sub_f32_e32 v29, v29, v38
	v_sub_f32_e32 v34, v34, v38
	v_sub_f32_e32 v30, v30, v38
	v_sub_f32_e32 v35, v35, v38
	v_sub_f32_e32 v31, v31, v38
	v_sub_f32_e32 v36, v36, v38
	v_sub_f32_e32 v32, v32, v38
	v_sub_f32_e32 v33, v33, v38
	s_nop 0
	v_exp_f32_e32 v62, v37
	v_exp_f32_e32 v37, v39
	v_exp_f32_e32 v38, v41
	v_exp_f32_e32 v39, v43
	v_exp_f32_e32 v41, v45
	v_exp_f32_e32 v43, v6
	v_exp_f32_e32 v45, v7
	v_exp_f32_e32 v80, v9
	v_exp_f32_e32 v112, v40
	v_exp_f32_e32 v113, v42
	v_exp_f32_e32 v114, v44
	v_exp_f32_e32 v115, v46
	v_exp_f32_e32 v116, v18
	v_exp_f32_e32 v117, v19
	v_exp_f32_e32 v118, v20
	v_exp_f32_e32 v119, v21
	v_exp_f32_e32 v120, v23
	v_exp_f32_e32 v121, v25
	v_exp_f32_e32 v122, v27
	v_exp_f32_e32 v123, v29
	s_waitcnt vmcnt(2) lgkmcnt(0)
	s_barrier
	v_exp_f32_e32 v63, v8
	v_exp_f32_e32 v104, v22
	v_exp_f32_e32 v105, v24
	v_exp_f32_e32 v106, v26
	v_exp_f32_e32 v107, v28
	v_exp_f32_e32 v108, v34
	v_exp_f32_e32 v109, v35
	v_exp_f32_e32 v110, v36
	v_exp_f32_e32 v111, v33
	v_exp_f32_e32 v132, v30
	v_exp_f32_e32 v133, v31
	v_exp_f32_e32 v134, v32
	ds_read_b64_tr_b16 v[54:55], v246 offset:24576
	ds_read_b64_tr_b16 v[56:57], v246 offset:25088
	s_waitcnt lgkmcnt(9)
	v_mfma_f32_32x32x16_f16 v[18:33], v[2:5], v[144:147], v[64:79]
	v_add_f32_e32 v6, v37, v38
	v_add_f32_e32 v6, v6, v39
	v_add_f32_e32 v6, v6, v41
	v_add_f32_e32 v6, v6, v43
	v_add_f32_e32 v34, v6, v45
	v_cvt_pk_f16_f32 v6, v37, v38
	v_cvt_pk_f16_f32 v7, v39, v41
	ds_read_b64_tr_b16 v[50:51], v246 offset:28672
	ds_read_b64_tr_b16 v[52:53], v246 offset:29184
	v_add_f32_e32 v2, v63, v34
	v_cvt_pk_f16_f32 v8, v43, v45
	s_waitcnt lgkmcnt(10)
	v_mfma_f32_32x32x16_f16 v[34:49], v[10:13], v[144:147], v[64:79]
	v_add_f32_e32 v2, v80, v2
	v_add_f32_e32 v2, v104, v2
	v_add_f32_e32 v2, v105, v2
	v_cvt_pk_f16_f32 v9, v63, v80
	ds_read_b64_tr_b16 v[80:81], v246 offset:25600
	ds_read_b64_tr_b16 v[82:83], v246 offset:26112
	s_waitcnt lgkmcnt(11)
	v_mfma_f32_32x32x16_f16 v[18:33], v[58:61], v[148:151], v[18:33]
	v_add_f32_e32 v2, v106, v2
	v_add_f32_e32 v2, v107, v2
	v_add_f32_e32 v2, v108, v2
	v_add_f32_e32 v10, v109, v2
	v_cvt_pk_f16_f32 v2, v104, v105
	v_cvt_pk_f16_f32 v3, v106, v107
	ds_read_b64_tr_b16 v[124:125], v246 offset:29696
	ds_read_b64_tr_b16 v[126:127], v246 offset:30208
	s_waitcnt lgkmcnt(12)
	v_mfma_f32_32x32x16_f16 v[34:49], v[84:87], v[148:151], v[34:49]
	v_add_f32_e32 v4, v110, v10
	v_add_f32_e32 v4, v62, v4
	v_add_f32_e32 v4, v112, v4
	v_add_f32_e32 v10, v113, v4
	v_cvt_pk_f16_f32 v4, v108, v109
	v_cvt_pk_f16_f32 v5, v110, v62
	ds_read_b64_tr_b16 v[128:129], v246 offset:26624
	ds_read_b64_tr_b16 v[130:131], v246 offset:27136
	s_waitcnt lgkmcnt(13)
	v_mfma_f32_32x32x16_f16 v[18:33], v[88:91], v[152:155], v[18:33]
	v_add_f32_e32 v10, v114, v10
	v_add_f32_e32 v10, v115, v10
	v_add_f32_e32 v10, v116, v10
	v_add_f32_e32 v58, v117, v10
	v_cvt_pk_f16_f32 v10, v112, v113
	v_cvt_pk_f16_f32 v11, v114, v115
	ds_read_b64_tr_b16 v[112:113], v246 offset:30720
	ds_read_b64_tr_b16 v[114:115], v246 offset:31232
	s_waitcnt lgkmcnt(14)
	v_mfma_f32_32x32x16_f16 v[34:49], v[92:95], v[152:155], v[34:49]
	v_add_f32_e32 v12, v118, v58
	v_add_f32_e32 v12, v119, v12
	v_add_f32_e32 v12, v120, v12
	v_add_f32_e32 v58, v121, v12
	v_cvt_pk_f16_f32 v12, v116, v117
	v_cvt_pk_f16_f32 v13, v118, v119
	ds_read_b64_tr_b16 v[116:117], v246 offset:27648
	ds_read_b64_tr_b16 v[118:119], v246 offset:28160
	s_waitcnt lgkmcnt(14)
	v_mfma_f32_32x32x16_f16 v[18:33], v[96:99], v[156:159], v[18:33]
	v_add_f32_e32 v58, v122, v58
	v_add_f32_e32 v58, v123, v58
	v_add_f32_e32 v58, v132, v58
	v_add_f32_e32 v58, v133, v58
	v_cvt_pk_f16_f32 v160, v120, v121
	v_cvt_pk_f16_f32 v161, v122, v123
	ds_read_b64_tr_b16 v[120:121], v246 offset:31744
	ds_read_b64_tr_b16 v[122:123], v246 offset:32256
	v_mfma_f32_32x32x16_f16 v[34:49], v[100:103], v[156:159], v[34:49]
	v_add_f32_e32 v58, v134, v58
	v_add_f32_e32 v58, v111, v58
	v_add_f32_e32 v58, 0, v58
	v_cvt_pk_f16_f32 v162, v132, v133
	v_cvt_pk_f16_f32 v163, v134, v111
	v_cndmask_b32_e64 v59, 0, 1, s[8:9]
	v_cmp_ne_u32_e64 s[38:39], 1, v59
	s_andn2_b64 vcc, exec, s[8:9]
	s_cbranch_vccnz .LBB0_468
	s_lshl_b32 s22, s28, 13
	s_mov_b32 s23, s59
	s_cmp_lg_u32 0, -1
	v_lshl_add_u64 v[60:61], v[218:219], 0, s[22:23]
	s_mov_b32 s22, 0xffff6000
	s_cselect_b32 s12, 0, 0
	s_mov_b32 s23, -1
	s_add_i32 s12, s12, s24
	v_lshl_add_u64 v[60:61], v[60:61], 0, s[22:23]
	s_addk_i32 s12, 0x2000
	s_mov_b32 s13, m0
	s_mov_b32 m0, s12
	s_nop 0
	global_load_lds_dwordx4 v[60:61], off
	s_mov_b32 m0, s13
